# v54 + HGRN2 chunk loop keeps the ws pointer in SGPRs instead of 2 LDS parameter reads per chunk
# baseline (speedup 1.0000x reference)
; #define GAS __attribute__((address_space(1)))
; #define F_state_hgrn F.in(5)
; template <int PART>
; __device__ __forceinline__ void prefetch(Pre& P, const GAS unsigned char* ws, size_t row0, int nvalid, int seg, int colb  , int trow  , int sgcol  ) {
;     const GAS _Float16* LF = (const GAS _Float16*)(ws + WS_LOGF) + row0 * 1024; const GAS bf16* QC = (const GAS bf16*)(ws + WS_QC) + row0 * 1024; const GAS bf16* KC = (const GAS bf16*)(ws + WS_KC) + row0 * 1024; const GAS bf16* IC = (const GAS bf16*)(ws + WS_IC) + row0 * 1024;
;     if (PART & 2) { const GAS bf16* SGC = (const GAS bf16*)(ws + WS_SGC) + row0 * 1024; const unsigned so = (unsigned)((trow < nvalid ? trow : 0) * 1024 + sgcol);
; #pragma unroll
;       for (int g = 0; g < 4; ++g) P.sg[g] = *(const GAS v2u*)(SGC + so + 8 * g); }
;     if (nvalid == 64) {
; #pragma unroll
;         for (int i = 0; i < 8; ++i) { const unsigned o = (unsigned)((seg * 8 + i) * 1024 + colb);
;             if (PART & 1) P.lf[i] = *(const GAS unsigned*)(LF + o);
;             if (PART & 2) { P.q[i] = *(const GAS unsigned*)(QC + o); P.k[i] = *(const GAS unsigned*)(KC + o); P.v[i] = *(const GAS unsigned*)(IC + o); } }
;     } else {
; #pragma unroll
;         for (int i = 0; i < 8; ++i) { const int t = seg * 8 + i; const unsigned o = (unsigned)(t * 1024 + colb);
;             if (t < nvalid) { if (PART & 1) P.lf[i] = *(const GAS unsigned*)(LF + o); if (PART & 2) { P.q[i] = *(const GAS unsigned*)(QC + o); P.k[i] = *(const GAS unsigned*)(KC + o); P.v[i] = *(const GAS unsigned*)(IC + o); } }
;             else { if (PART & 1) P.lf[i] = 0u; if (PART & 2) { P.q[i] = 0u; P.k[i] = 0u; P.v[i] = 0u; } } }
;     }
; __device__ __forceinline__ void chain(Frame& F, int layer, bool sample, int b, int h) {
;     ...
;     const int lane = tid & 63, wave = F.wave, seg = wave; int kp = tid & 63, l31 = lane & 31, hh = lane >> 5;
;     const int L = sample ? DSEQ : LP, nchunks = (L + 63) / 64;
;     const size_t rowbase = sample ? (size_t)MPAD + (size_t)b * DSEQ : (size_t)b * LP;
;     const int colb = h * 128 + 2 * kp;
;     GAS bf16* YC = (GAS bf16*)(F.wsp() + WS_Y) + (size_t)2 * MTOT * 1024;
;     const int kb = wave >> 1, vb0 = 2 * (wave & 1);
;     f32x16 S[2];
;     if (sample) { const GAS float* s0 = F_state_hgrn + (((size_t)layer * DBATCH + b) * 8 + h) * 16384;
; #pragma unroll
;         for (int vbi = 0; vbi < 2; ++vbi)
; #pragma unroll
.LBB0_759:
	s_or_b64 exec, exec, s[58:59]
	v_and_b32_e32 v93, 63, v0
	v_mov_b32_e32 v0, s18
	ds_read_b64 v[0:1], v0
	s_lshl_b32 s20, s12, 7
	s_and_b64 s[16:17], s[56:57], exec
	s_cselect_b32 s13, 64, 0x810
	s_add_i32 s14, s13, 63
	s_lshr_b32 s14, s14, 6
	s_waitcnt lgkmcnt(0)
	v_readfirstlane_b32 s17, v0
	s_mov_b32 s98, s17
	s_or_b32 s74, s20, s97
	s_lshl_b64 s[56:57], s[36:37], 10
	s_lshl_b64 s[58:59], s[36:37], 11
	v_readfirstlane_b32 s16, v1
	s_mov_b32 s99, s16
	s_add_u32 s60, s17, s58
	s_addc_u32 s61, s16, s59
	s_add_u32 s16, s60, 0x18f80000
	s_addc_u32 s17, s61, 0
	s_add_u32 s52, s60, 0x14680000
	s_addc_u32 s53, s61, 0
	v_lshl_or_b32 v24, v93, 1, s20
	v_readlane_b32 s20, v242, 24
	s_add_u32 s62, s60, 0x16b00000
	s_addc_u32 s63, s61, 0
	v_or_b32_e32 v66, s20, v24
	v_or_b32_e32 v172, 0x1c00, v66
	s_add_u32 s64, s60, 0x24600000
	v_or_b32_e32 v74, 0x1400, v66
	v_mov_b32_e32 v75, v173
	v_or_b32_e32 v76, 0x1800, v66
	v_mov_b32_e32 v77, v173
	v_lshlrev_b64 v[0:1], 1, v[172:173]
	s_addc_u32 s65, s61, 0
	v_or_b32_e32 v70, 0xc00, v66
	v_mov_b32_e32 v71, v173
	v_or_b32_e32 v72, 0x1000, v66
	v_mov_b32_e32 v73, v173
	v_lshl_add_u64 v[2:3], s[16:17], 0, v[0:1]
	v_lshl_add_u64 v[4:5], s[52:53], 0, v[0:1]
	v_lshl_add_u64 v[6:7], s[62:63], 0, v[0:1]
	v_lshl_add_u64 v[0:1], s[64:65], 0, v[0:1]
	v_lshlrev_b64 v[80:81], 1, v[76:77]
	v_lshlrev_b64 v[82:83], 1, v[74:75]
	v_mov_b32_e32 v67, v173
	v_or_b32_e32 v68, 0x800, v66
	v_mov_b32_e32 v69, v173
	v_lshl_add_u64 v[8:9], s[16:17], 0, v[80:81]
	v_lshl_add_u64 v[10:11], s[52:53], 0, v[80:81]
	v_lshl_add_u64 v[12:13], s[62:63], 0, v[80:81]
	v_lshl_add_u64 v[14:15], s[64:65], 0, v[80:81]
	global_load_dword v143, v[2:3], off
	global_load_dword v142, v[4:5], off
	global_load_dword v141, v[6:7], off
	global_load_dword v129, v[0:1], off
	global_load_dword v140, v[8:9], off
	global_load_dword v139, v[10:11], off
	global_load_dword v138, v[12:13], off
	global_load_dword v118, v[14:15], off
	v_lshl_add_u64 v[0:1], s[16:17], 0, v[82:83]
	v_lshlrev_b64 v[84:85], 1, v[72:73]
	v_lshlrev_b64 v[86:87], 1, v[70:71]
	v_lshl_add_u64 v[2:3], s[52:53], 0, v[82:83]
	v_lshl_add_u64 v[4:5], s[62:63], 0, v[82:83]
	v_lshl_add_u64 v[6:7], s[64:65], 0, v[82:83]
	v_lshl_add_u64 v[8:9], s[16:17], 0, v[84:85]
	v_lshl_add_u64 v[10:11], s[52:53], 0, v[84:85]
	v_lshl_add_u64 v[12:13], s[62:63], 0, v[84:85]
	v_lshl_add_u64 v[14:15], s[64:65], 0, v[84:85]
	global_load_dword v136, v[0:1], off
	global_load_dword v137, v[2:3], off
	global_load_dword v135, v[4:5], off
	global_load_dword v117, v[6:7], off
	global_load_dword v132, v[8:9], off
	global_load_dword v133, v[10:11], off
	global_load_dword v134, v[12:13], off
	global_load_dword v101, v[14:15], off
	v_lshl_add_u64 v[0:1], s[16:17], 0, v[86:87]
	v_lshlrev_b64 v[88:89], 1, v[68:69]
	v_lshlrev_b64 v[90:91], 1, v[66:67]
	v_lshl_add_u64 v[2:3], s[52:53], 0, v[86:87]
	v_lshl_add_u64 v[4:5], s[62:63], 0, v[86:87]
	v_lshl_add_u64 v[6:7], s[64:65], 0, v[86:87]
	v_lshl_add_u64 v[8:9], s[16:17], 0, v[88:89]
	v_lshl_add_u64 v[10:11], s[52:53], 0, v[88:89]
	v_lshl_add_u64 v[12:13], s[62:63], 0, v[88:89]
	v_lshl_add_u64 v[14:15], s[64:65], 0, v[88:89]
	global_load_dword v130, v[0:1], off
	global_load_dword v131, v[2:3], off
	global_load_dword v128, v[4:5], off
	global_load_dword v103, v[6:7], off
	global_load_dword v127, v[8:9], off
	global_load_dword v126, v[10:11], off
	global_load_dword v125, v[12:13], off
	global_load_dword v99, v[14:15], off
	v_lshl_add_u64 v[0:1], s[16:17], 0, v[90:91]
	v_lshl_add_u64 v[2:3], s[52:53], 0, v[90:91]
	v_lshl_add_u64 v[4:5], s[62:63], 0, v[90:91]
	v_lshl_add_u64 v[6:7], s[64:65], 0, v[90:91]
	global_load_dword v123, v[0:1], off offset:2048
	global_load_dword v124, v[2:3], off offset:2048
	global_load_dword v119, v[4:5], off offset:2048
	global_load_dword v97, v[6:7], off offset:2048
	global_load_dword v95, v[6:7], off
	global_load_dword v120, v[4:5], off
	global_load_dword v121, v[2:3], off
	global_load_dword v122, v[0:1], off
	v_or_b32_e32 v0, s94, v32
	v_readlane_b32 s16, v242, 25
	v_lshlrev_b32_e32 v0, 10, v0
	v_readlane_b32 s17, v242, 26
	v_lshlrev_b32_e32 v1, 2, v33
	v_mov_b64_e32 v[78:79], v[172:173]
	v_cndmask_b32_e64 v0, 0, v0, s[16:17]
	v_or3_b32 v0, v0, v1, s74
	v_lshlrev_b32_e32 v172, 1, v0
	v_lshl_add_u64 v[0:1], s[60:61], 0, v[172:173]
	s_mov_b64 s[16:17], 0x1b400000
	v_lshl_add_u64 v[2:3], v[0:1], 0, s[16:17]
	s_mov_b32 s16, 0x1b400000
	v_add_co_u32_e32 v0, vcc, s16, v0
	v_readlane_b32 s16, v242, 27
	s_nop 0
	v_addc_co_u32_e32 v1, vcc, 0, v1, vcc
	global_load_dwordx2 v[16:17], v[2:3], off offset:48
	global_load_dwordx2 v[22:23], v[0:1], off
	global_load_dwordx2 v[18:19], v[2:3], off offset:32
	global_load_dwordx2 v[20:21], v[2:3], off offset:16
	v_or_b32_e32 v92, s16, v24
	v_readlane_b32 s16, v242, 28
	s_mov_b32 s62, 0
	s_nop 0
	v_or_b32_e32 v94, s16, v24
	v_readlane_b32 s16, v242, 29
	s_nop 1
	v_or_b32_e32 v96, s16, v24
	v_readlane_b32 s16, v242, 30
	s_nop 1
	v_or_b32_e32 v98, s16, v24
	v_readlane_b32 s16, v242, 31
	s_nop 1
	v_or_b32_e32 v100, s16, v24
	v_readlane_b32 s16, v242, 32
	s_nop 1
	v_or_b32_e32 v102, s16, v24
	v_readlane_b32 s16, v242, 33
	s_nop 1
	v_or_b32_e32 v172, s16, v24
	s_lshl_b32 s16, s12, 8
	s_add_u32 s16, s24, s16
	s_addc_u32 s15, s15, 0
	s_lshl_b32 s17, s97, 1
	s_add_u32 s16, s16, s17
	s_addc_u32 s15, s15, 0
	s_add_u32 s60, s16, 0x2d800000
	v_mov_b64_e32 v[104:105], v[172:173]
	s_addc_u32 s61, s15, 0
	s_waitcnt vmcnt(0)
	s_branch .LBB0_761

; #define GAS __attribute__((address_space(1)))
; #define LAS __attribute__((address_space(3)))
;     __device__ __forceinline__ GAS unsigned char* wsp() const { return (GAS unsigned char*)rd(18); }
; template <int PART>
; __device__ __forceinline__ void prefetch(Pre& P, const GAS unsigned char* ws, size_t row0, int nvalid, int seg, int colb  , int trow  , int sgcol  ) {
;     ...
;     if (nvalid == 64) {
; #pragma unroll
;         for (int i = 0; i < 8; ++i) { const unsigned o = (unsigned)((seg * 8 + i) * 1024 + colb);
;             if (PART & 1) P.lf[i] = *(const GAS unsigned*)(LF + o);
;             if (PART & 2) { P.q[i] = *(const GAS unsigned*)(QC + o); P.k[i] = *(const GAS unsigned*)(KC + o); P.v[i] = *(const GAS unsigned*)(IC + o); } }
;     } else {
; #pragma unroll
;         for (int i = 0; i < 8; ++i) { const int t = seg * 8 + i; const unsigned o = (unsigned)(t * 1024 + colb);
;             if (t < nvalid) { if (PART & 1) P.lf[i] = *(const GAS unsigned*)(LF + o); if (PART & 2) { P.q[i] = *(const GAS unsigned*)(QC + o); P.k[i] = *(const GAS unsigned*)(KC + o); P.v[i] = *(const GAS unsigned*)(IC + o); } }
; __device__ __forceinline__ void chain(Frame& F, int layer, bool sample, int b, int h) {
;     ...
;         float c0[8], c1[8]; { float a0 = 0.f, a1 = 0.f;
; #pragma unroll
;             for (int i = 0; i < 8; ++i) { const pg8::h16x2 hv = __builtin_bit_cast(pg8::h16x2, P.lf[i]); a0 += (float)hv.x; a1 += (float)hv.y; c0[i] = a0; c1[i] = a1; }
;             *(LAS f32x2*)(lds + L_SEG + (seg * 128 + 2 * kp) * 4) = (f32x2){a0, a1}; }
;         if (c + 1 < nchunks) prefetch<1>(P, F.wsp(), rowbase + (size_t)64 * (c + 1), min(64, L - 64 * (c + 1)), seg, colb, 32 * otb + l31, h * 128 + 32 * ovb + 4 * hh);
.LBB0_761:
	s_waitcnt vmcnt(32)
	v_cvt_f32_f16_sdwa v1, v95 dst_sel:DWORD dst_unused:UNUSED_PAD src0_sel:WORD_1
	v_cvt_f32_f16_e32 v0, v95
	v_cvt_f32_f16_sdwa v3, v97 dst_sel:DWORD dst_unused:UNUSED_PAD src0_sel:WORD_1
	v_cvt_f32_f16_e32 v2, v97
	v_cvt_f32_f16_sdwa v5, v99 dst_sel:DWORD dst_unused:UNUSED_PAD src0_sel:WORD_1
	v_cvt_f32_f16_e32 v4, v99
	v_cvt_f32_f16_sdwa v7, v103 dst_sel:DWORD dst_unused:UNUSED_PAD src0_sel:WORD_1
	v_cvt_f32_f16_e32 v6, v103
	v_pk_add_f32 v[30:31], v[0:1], 0 op_sel_hi:[1,0]
	v_cvt_f32_f16_sdwa v1, v101 dst_sel:DWORD dst_unused:UNUSED_PAD src0_sel:WORD_1
	v_cvt_f32_f16_e32 v0, v101
	v_pk_add_f32 v[28:29], v[30:31], v[2:3]
	v_cvt_f32_f16_sdwa v3, v117 dst_sel:DWORD dst_unused:UNUSED_PAD src0_sel:WORD_1
	v_cvt_f32_f16_e32 v2, v117
	v_pk_add_f32 v[26:27], v[28:29], v[4:5]
	v_cvt_f32_f16_sdwa v5, v118 dst_sel:DWORD dst_unused:UNUSED_PAD src0_sel:WORD_1
	v_cvt_f32_f16_e32 v4, v118
	v_pk_add_f32 v[24:25], v[26:27], v[6:7]
	v_cvt_f32_f16_sdwa v7, v129 dst_sel:DWORD dst_unused:UNUSED_PAD src0_sel:WORD_1
	v_cvt_f32_f16_e32 v6, v129
	v_pk_add_f32 v[14:15], v[24:25], v[0:1]
	s_add_i32 s20, s62, 1
	v_pk_add_f32 v[12:13], v[14:15], v[2:3]
	s_cmp_lt_u32 s20, s14
	v_pk_add_f32 v[10:11], v[12:13], v[4:5]
	v_lshlrev_b32_e32 v2, 3, v93
	v_pk_add_f32 v[8:9], v[10:11], v[6:7]
	v_add_u32_e32 v0, s22, v2
	s_cselect_b64 s[64:65], -1, 0
	s_cmp_ge_u32 s20, s14
	ds_write_b64 v0, v[8:9]
	s_cbranch_scc1 .Lch_skipL
	s_lshl_b32 s15, s20, 6
	s_sub_i32 s15, s13, s15
	s_lshl_b64 s[16:17], s[20:21], 17
	s_mov_b32 s25, s98
	s_mov_b32 s24, s99
	s_add_u32 s16, s25, s16
	s_addc_u32 s17, s24, s17
	s_add_u32 s16, s16, s58
	s_addc_u32 s17, s17, s59
	s_add_u32 s66, s16, 0x24600000
	s_addc_u32 s67, s17, 0
	s_cmp_gt_i32 s15, 63
	s_cbranch_scc1 .LBB0_771
	s_min_i32 s15, s15, 64
	s_cmp_lt_i32 s23, s15
	s_cbranch_scc0 .LBB0_772
	v_lshl_add_u64 v[0:1], v[66:67], 1, s[66:67]
	global_load_dword v95, v[0:1], off
	s_cmp_ge_i32 s28, s15
	s_cbranch_scc0 .LBB0_773

; #define GAS __attribute__((address_space(1)))
;     __device__ __forceinline__ GAS unsigned char* wsp() const { return (GAS unsigned char*)rd(18); }
; template <int PART>
; __device__ __forceinline__ void prefetch(Pre& P, const GAS unsigned char* ws, size_t row0, int nvalid, int seg, int colb  , int trow  , int sgcol  ) {
;     const GAS _Float16* LF = (const GAS _Float16*)(ws + WS_LOGF) + row0 * 1024; const GAS bf16* QC = (const GAS bf16*)(ws + WS_QC) + row0 * 1024; const GAS bf16* KC = (const GAS bf16*)(ws + WS_KC) + row0 * 1024; const GAS bf16* IC = (const GAS bf16*)(ws + WS_IC) + row0 * 1024;
;     if (PART & 2) { const GAS bf16* SGC = (const GAS bf16*)(ws + WS_SGC) + row0 * 1024; const unsigned so = (unsigned)((trow < nvalid ? trow : 0) * 1024 + sgcol);
; #pragma unroll
;       for (int g = 0; g < 4; ++g) P.sg[g] = *(const GAS v2u*)(SGC + so + 8 * g); }
;     if (nvalid == 64) {
; #pragma unroll
;         for (int i = 0; i < 8; ++i) { const unsigned o = (unsigned)((seg * 8 + i) * 1024 + colb);
;             if (PART & 1) P.lf[i] = *(const GAS unsigned*)(LF + o);
;             if (PART & 2) { P.q[i] = *(const GAS unsigned*)(QC + o); P.k[i] = *(const GAS unsigned*)(KC + o); P.v[i] = *(const GAS unsigned*)(IC + o); } }
;     } else {
; #pragma unroll
;         for (int i = 0; i < 8; ++i) { const int t = seg * 8 + i; const unsigned o = (unsigned)(t * 1024 + colb);
;             if (t < nvalid) { if (PART & 1) P.lf[i] = *(const GAS unsigned*)(LF + o); if (PART & 2) { P.q[i] = *(const GAS unsigned*)(QC + o); P.k[i] = *(const GAS unsigned*)(KC + o); P.v[i] = *(const GAS unsigned*)(IC + o); } }
;             else { if (PART & 1) P.lf[i] = 0u; if (PART & 2) { P.q[i] = 0u; P.k[i] = 0u; P.v[i] = 0u; } } }
;     }
; __device__ __forceinline__ void chain(Frame& F, int layer, bool sample, int b, int h) {
;     ...
;         v2u sg[4] = {P.sg[0], P.sg[1], P.sg[2], P.sg[3]};
;         if (c + 1 < nchunks) prefetch<2>(P, F.wsp(), rowbase + (size_t)64 * (c + 1), min(64, L - 64 * (c + 1)), seg, colb, 32 * otb + l31, h * 128 + 32 * ovb + 4 * hh);
.LBB0_786:
	s_andn2_b64 vcc, exec, s[64:65]
	v_add_u32_e32 v24, s94, v32
	v_lshlrev_b32_e32 v114, 2, v33
	s_waitcnt vmcnt(12)
	v_mov_b64_e32 v[106:107], v[16:17]
	s_waitcnt vmcnt(12)
	v_mov_b64_e32 v[108:109], v[18:19]
	s_waitcnt vmcnt(12)
	v_mov_b64_e32 v[110:111], v[20:21]
	v_mov_b64_e32 v[112:113], v[22:23]
	s_cbranch_vccnz .LBB0_807
	s_lshl_b32 s15, s20, 6
	s_sub_i32 s24, s13, s15
	s_min_i32 s15, s24, 64
	s_lshl_b64 s[16:17], s[20:21], 16
	s_add_u32 s16, s16, s56
	s_addc_u32 s17, s17, s57
	s_mov_b32 s25, s99
	s_mov_b32 s52, s98
	s_lshl_b64 s[16:17], s[16:17], 1
	v_lshlrev_b32_e32 v1, 10, v24
	v_cmp_gt_i32_e32 vcc, s15, v24
	v_lshlrev_b32_e32 v0, 2, v33
	s_add_u32 s16, s52, s16
	v_cndmask_b32_e32 v1, 0, v1, vcc
	v_add3_u32 v172, v0, s74, v1
	s_addc_u32 s17, s25, s17
	v_lshl_add_u64 v[0:1], v[172:173], 1, s[16:17]
	s_mov_b64 s[52:53], 0x1b400000
	s_mov_b32 s25, 0x1b400000
	v_lshl_add_u64 v[2:3], v[0:1], 0, s[52:53]
	v_add_co_u32_e32 v0, vcc, s25, v0
	s_add_u32 s68, s16, 0x16b00000
	s_nop 0
	v_addc_co_u32_e32 v1, vcc, 0, v1, vcc
	global_load_dwordx2 v[112:113], v[0:1], off
	global_load_dwordx2 v[110:111], v[2:3], off offset:16
	global_load_dwordx2 v[108:109], v[2:3], off offset:32
	global_load_dwordx2 v[106:107], v[2:3], off offset:48
	s_addc_u32 s69, s17, 0
	s_add_u32 s66, s16, 0x14680000
	s_addc_u32 s67, s17, 0
	s_add_u32 s64, s16, 0x18f80000
	s_addc_u32 s65, s17, 0
	s_cmp_gt_i32 s24, 63
	s_cbranch_scc1 .LBB0_803
	v_mov_b32_e32 v119, 0
	s_cmp_lt_i32 s23, s15
	v_mov_b32_e32 v120, 0
	v_mov_b32_e32 v121, 0
	v_mov_b32_e32 v122, 0
	s_cbranch_scc0 .LBB0_790
	v_lshl_add_u64 v[0:1], s[68:69], 0, v[90:91]
	v_lshl_add_u64 v[2:3], s[66:67], 0, v[90:91]
	v_lshl_add_u64 v[4:5], s[64:65], 0, v[90:91]
	global_load_dword v120, v[0:1], off
	global_load_dword v121, v[2:3], off
	global_load_dword v122, v[4:5], off
